# MLA latent tile loop: K/V staging block moved to head of stage Y, row-sum adds spread through the PV MFMA gaps
# speedup vs baseline: 1.0027x; 1.0027x over previous
; #define LAS __attribute__((address_space(3)))
; __device__ __forceinline__ unsigned pk2(float lo, float hi) { return pg8::pkbf(lo, hi); }
; __device__ __forceinline__ float fexp2(float x) { return __builtin_amdgcn_exp2f(x); }
; template <int DV, bool MASK>
; __device__ __forceinline__ void attn_softmax(f32x16 (&p)[2], f32x16 (&o)[DV / 32], float& m, float& l, float cs, int hi, int dq) {
;     ...
;             const float e0 = fexp2(fmaf(p[kvb][e], cs, -m)), e1 = fexp2(fmaf(p[kvb][e + 1], cs, -m)), e2 = fexp2(fmaf(p[kvb][e + 2], cs, -m)), e3 = fexp2(fmaf(p[kvb][e + 3], cs, -m));
;             p[kvb][e] = e0; p[kvb][e + 1] = e1; p[kvb][e + 2] = e2; p[kvb][e + 3] = e3; ls0 += e0; ls1 += e1; ls2 += e2; ls3 += e3; }
;     l += (ls0 + ls1) + (ls2 + ls3);
; }
; template <int DV, int VRB>
; __device__ __forceinline__ void attn_pv(LAS const unsigned char* Vt, const f32x16 (&p)[2], f32x16 (&o)[DV / 32], int vtb) {
;     constexpr int ND = DV / 32;
;     LAS const unsigned char* vb = Vt + vtb;
;     bf16x8 pf[4];
; #pragma unroll
;     for (int i = 0; i < 4; ++i) { const int kvb = i >> 1, s = i & 1;
;         v4u pw; pw.x = pk2(p[kvb][8 * s + 0], p[kvb][8 * s + 1]); pw.y = pk2(p[kvb][8 * s + 2], p[kvb][8 * s + 3]); pw.z = pk2(p[kvb][8 * s + 4], p[kvb][8 * s + 5]); pw.w = pk2(p[kvb][8 * s + 6], p[kvb][8 * s + 7]);
;         pf[i] = __builtin_bit_cast(bf16x8, pw); }
;     s16x4 va[2 * ND], vbq[2 * ND];
; __device__ __forceinline__ void mla_unit(const bf16* QM, const bf16* KVM, const bf16* KR, bf16* Y, int b, int h, int qrow0, int ntiles, bool latent, LAS unsigned char* L, int tid_in) {
;     ...
;     const int half = wave >> 2;
;     MLA_LOAD(0); MLA_STORE(0);
;     if (ntiles > 1) { MLA_LOAD(1); MLA_STORE(1); }
;     __syncthreads();
;     if (half) __builtin_amdgcn_s_barrier();
;     if (ntiles > 2) MLA_LOAD(2);
;     int bcur = 0, bst = 2;
;     for (int t = 0; t < ntiles; ++t) {
;         LAS const unsigned char* Kt = L + bcur * MLA_BUF;
;         f32x16 p[2];
;         __builtin_amdgcn_sched_barrier(0);
;         attn_scores<192, MLA_KSB>(Kt, qf, p, r32, hi);
;         __syncthreads();
;         attn_softmax<128, false>(p, o, m, l, cs, hi, 0);
;         attn_pv<128, MLA_VRB>(Kt + MLA_KT, p, o, vtb);
;         if (t + 2 < ntiles) { MLA_STORE(bst); if (t + 3 < ntiles) MLA_LOAD(t + 3); }
.LBB0_973:
	v_fma_f32 v34, v112, s44, -v32
	v_fma_f32 v112, v126, s44, -v32
	v_add3_u32 v126, s12, v199, v206
	ds_read_b64_tr_b16 v[208:209], v126 offset:25600
	ds_read_b64_tr_b16 v[212:213], v126 offset:25664
	ds_read_b64_tr_b16 v[216:217], v126 offset:25728
	ds_read_b64_tr_b16 v[220:221], v126 offset:25792
	ds_read_b64_tr_b16 v[210:211], v126 offset:28160
	ds_read_b64_tr_b16 v[214:215], v126 offset:28224
	ds_read_b64_tr_b16 v[218:219], v126 offset:28288
	ds_read_b64_tr_b16 v[222:223], v126 offset:28352
	s_cmpk_gt_u32 s10, 0x81
	s_cbranch_scc1 .Lmla_stage_done
	s_mul_i32 s12, s9, 0xb400
	v_add_u32_e32 v36, s12, v198
	s_waitcnt vmcnt(0)
	ds_write_b128 v36, v[172:175]
	ds_write_b128 v36, v[168:171] offset:12800
	v_add_u32_e32 v36, s12, v200
	ds_write_b128 v36, v[164:167] offset:256
	v_add_u32_e32 v36, s12, v31
	s_cmp_eq_u32 s4, 0x1020000
	ds_write_b128 v36, v[180:183] offset:25600
	ds_write_b128 v36, v[176:179] offset:35840
	s_cbranch_scc1 .Lmla_stage_done
	v_lshl_add_u64 v[36:37], v[204:205], 0, s[4:5]
	v_add_co_u32_e32 v38, vcc, 0x3d260000, v36
	s_nop 1
	v_addc_co_u32_e32 v39, vcc, 0, v37, vcc
	v_add_co_u32_e32 v36, vcc, 0x3d270000, v36
	s_nop 1
	v_addc_co_u32_e32 v37, vcc, 0, v37, vcc
	global_load_dwordx4 v[164:167], v[202:203], off
	global_load_dwordx4 v[172:175], v[38:39], off
	global_load_dwordx4 v[180:183], v[38:39], off offset:256
	global_load_dwordx4 v[168:171], v[36:37], off
	global_load_dwordx4 v[176:179], v[36:37], off offset:256
; #define LAS __attribute__((address_space(3)))
; __device__ __forceinline__ unsigned pk2(float lo, float hi) { return pg8::pkbf(lo, hi); }
; __device__ __forceinline__ float fexp2(float x) { return __builtin_amdgcn_exp2f(x); }
; #define SCHED_FENCE() __builtin_amdgcn_sched_barrier(0)
; template <int DV, bool MASK>
; __device__ __forceinline__ void attn_softmax(f32x16 (&p)[2], f32x16 (&o)[DV / 32], float& m, float& l, float cs, int hi, int dq) {
;     ...
;     float ls0 = 0.f, ls1 = 0.f, ls2 = 0.f, ls3 = 0.f;
; #pragma unroll
;     for (int kvb = 0; kvb < 2; ++kvb)
; #pragma unroll
;         for (int e = 0; e < 16; e += 4) {
;             const float e0 = fexp2(fmaf(p[kvb][e], cs, -m)), e1 = fexp2(fmaf(p[kvb][e + 1], cs, -m)), e2 = fexp2(fmaf(p[kvb][e + 2], cs, -m)), e3 = fexp2(fmaf(p[kvb][e + 3], cs, -m));
;             p[kvb][e] = e0; p[kvb][e + 1] = e1; p[kvb][e + 2] = e2; p[kvb][e + 3] = e3; ls0 += e0; ls1 += e1; ls2 += e2; ls3 += e3; }
;     l += (ls0 + ls1) + (ls2 + ls3);
; }
; template <int DV, int VRB>
; __device__ __forceinline__ void attn_pv(LAS const unsigned char* Vt, const f32x16 (&p)[2], f32x16 (&o)[DV / 32], int vtb) {
;     constexpr int ND = DV / 32;
;     LAS const unsigned char* vb = Vt + vtb;
;     bf16x8 pf[4];
; #pragma unroll
;     for (int i = 0; i < 4; ++i) { const int kvb = i >> 1, s = i & 1;
;         v4u pw; pw.x = pk2(p[kvb][8 * s + 0], p[kvb][8 * s + 1]); pw.y = pk2(p[kvb][8 * s + 2], p[kvb][8 * s + 3]); pw.z = pk2(p[kvb][8 * s + 4], p[kvb][8 * s + 5]); pw.w = pk2(p[kvb][8 * s + 6], p[kvb][8 * s + 7]);
;         pf[i] = __builtin_bit_cast(bf16x8, pw); }
;     s16x4 va[2 * ND], vbq[2 * ND];
;     ...
;     PV_LOAD(va, 0); SCHED_FENCE();
;     PV_LOAD(vbq, 1); PV_MMA(va, 0); SCHED_FENCE();
;     PV_LOAD(va, 2); PV_MMA(vbq, 1); SCHED_FENCE();
;     PV_LOAD(vbq, 3); PV_MMA(va, 2); SCHED_FENCE();
;     PV_MMA(vbq, 3); SCHED_FENCE();
; __device__ __forceinline__ void mla_unit(const bf16* QM, const bf16* KVM, const bf16* KR, bf16* Y, int b, int h, int qrow0, int ntiles, bool latent, LAS unsigned char* L, int tid_in) {
;     ...
;         if (t + 2 < ntiles) { MLA_STORE(bst); if (t + 3 < ntiles) MLA_LOAD(t + 3); }
;         __syncthreads();
;         bcur = bcur == 2 ? 0 : bcur + 1; bst = bst == 2 ? 0 : bst + 1;
.Lmla_stage_done:
	v_fma_f32 v35, v113, s44, -v32
	v_fma_f32 v36, v114, s44, -v32
	v_fma_f32 v37, v115, s44, -v32
	v_fma_f32 v38, v116, s44, -v32
	v_fma_f32 v39, v117, s44, -v32
	v_fma_f32 v40, v118, s44, -v32
	v_fma_f32 v41, v119, s44, -v32
	v_fma_f32 v42, v120, s44, -v32
	v_fma_f32 v43, v121, s44, -v32
	v_fma_f32 v44, v122, s44, -v32
	v_fma_f32 v45, v123, s44, -v32
	v_fma_f32 v46, v124, s44, -v32
	v_fma_f32 v47, v125, s44, -v32
	v_fma_f32 v113, v127, s44, -v32
	v_fma_f32 v96, v96, s44, -v32
	v_fma_f32 v97, v97, s44, -v32
	v_fma_f32 v98, v98, s44, -v32
	v_fma_f32 v99, v99, s44, -v32
	v_fma_f32 v100, v100, s44, -v32
	v_fma_f32 v101, v101, s44, -v32
	v_fma_f32 v102, v102, s44, -v32
	v_fma_f32 v103, v103, s44, -v32
	v_fma_f32 v104, v104, s44, -v32
	v_fma_f32 v105, v105, s44, -v32
	v_fma_f32 v106, v106, s44, -v32
	v_fma_f32 v107, v107, s44, -v32
	v_fma_f32 v108, v108, s44, -v32
	v_fma_f32 v109, v109, s44, -v32
	v_fma_f32 v110, v110, s44, -v32
	v_fma_f32 v111, v111, s44, -v32
	v_exp_f32_e32 v34, v34
	v_exp_f32_e32 v35, v35
	v_exp_f32_e32 v36, v36
	v_exp_f32_e32 v37, v37
	v_exp_f32_e32 v38, v38
	v_exp_f32_e32 v39, v39
	v_exp_f32_e32 v40, v40
	v_exp_f32_e32 v41, v41
	v_exp_f32_e32 v42, v42
	v_exp_f32_e32 v43, v43
	v_exp_f32_e32 v44, v44
	v_exp_f32_e32 v45, v45
	v_exp_f32_e32 v46, v46
	v_exp_f32_e32 v47, v47
	v_exp_f32_e32 v112, v112
	v_exp_f32_e32 v113, v113
	v_exp_f32_e32 v96, v96
	v_exp_f32_e32 v97, v97
	v_exp_f32_e32 v98, v98
	v_exp_f32_e32 v99, v99
	v_exp_f32_e32 v100, v100
	v_exp_f32_e32 v101, v101
	v_exp_f32_e32 v102, v102
	v_exp_f32_e32 v103, v103
	v_exp_f32_e32 v104, v104
	v_exp_f32_e32 v105, v105
	v_exp_f32_e32 v106, v106
	v_exp_f32_e32 v107, v107
	v_exp_f32_e32 v108, v108
	v_exp_f32_e32 v109, v109
	v_exp_f32_e32 v110, v110
	v_exp_f32_e32 v111, v111
	v_cvt_pk_bf16_f32 v114, v34, v35
	v_cvt_pk_bf16_f32 v115, v36, v37
	v_cvt_pk_bf16_f32 v116, v38, v39
	v_cvt_pk_bf16_f32 v117, v40, v41
	v_cvt_pk_bf16_f32 v118, v42, v43
	v_cvt_pk_bf16_f32 v119, v44, v45
	v_cvt_pk_bf16_f32 v120, v46, v47
	v_cvt_pk_bf16_f32 v121, v112, v113
	v_cvt_pk_bf16_f32 v122, v96, v97
	v_cvt_pk_bf16_f32 v123, v98, v99
	v_cvt_pk_bf16_f32 v124, v100, v101
	v_cvt_pk_bf16_f32 v125, v102, v103
	v_cvt_pk_bf16_f32 v224, v104, v105
	v_cvt_pk_bf16_f32 v225, v106, v107
	v_cvt_pk_bf16_f32 v226, v108, v109
	v_cvt_pk_bf16_f32 v227, v110, v111
	s_waitcnt lgkmcnt(3)
	v_mfma_f32_32x32x16_bf16 v[80:95], v[208:211], v[114:117], v[80:95]
	v_add_f32_e32 v34, 0, v34
	v_add_f32_e32 v35, 0, v35
	v_add_f32_e32 v36, 0, v36
	s_waitcnt lgkmcnt(2)
	v_mfma_f32_32x32x16_bf16 v[64:79], v[212:215], v[114:117], v[64:79]
	v_add_f32_e32 v37, 0, v37
	v_add_f32_e32 v34, v38, v34
	v_add_f32_e32 v35, v39, v35
	s_waitcnt lgkmcnt(1)
	v_mfma_f32_32x32x16_bf16 v[48:63], v[216:219], v[114:117], v[48:63]
	ds_read_b64_tr_b16 v[208:209], v126 offset:30720
	ds_read_b64_tr_b16 v[212:213], v126 offset:30784
	ds_read_b64_tr_b16 v[216:217], v126 offset:30848
	ds_read_b64_tr_b16 v[240:241], v126 offset:30912
	ds_read_b64_tr_b16 v[210:211], v126 offset:33280
	ds_read_b64_tr_b16 v[214:215], v126 offset:33344
	ds_read_b64_tr_b16 v[218:219], v126 offset:33408
	ds_read_b64_tr_b16 v[242:243], v126 offset:33472
	s_waitcnt lgkmcnt(8)
	v_mfma_f32_32x32x16_bf16 v[2:17], v[220:223], v[114:117], v[2:17]
	v_add_f32_e32 v36, v40, v36
	v_add_f32_e32 v37, v41, v37
	v_add_f32_e32 v34, v42, v34
	s_waitcnt lgkmcnt(3)
	v_mfma_f32_32x32x16_bf16 v[80:95], v[208:211], v[118:121], v[80:95]
	v_add_f32_e32 v35, v43, v35
	v_add_f32_e32 v36, v44, v36
	v_add_f32_e32 v37, v45, v37
	s_waitcnt lgkmcnt(2)
	v_mfma_f32_32x32x16_bf16 v[64:79], v[212:215], v[118:121], v[64:79]
	v_add_f32_e32 v34, v46, v34
	v_add_f32_e32 v35, v47, v35
	v_add_f32_e32 v36, v112, v36
	s_waitcnt lgkmcnt(1)
	v_mfma_f32_32x32x16_bf16 v[48:63], v[216:219], v[118:121], v[48:63]
	ds_read_b64_tr_b16 v[114:115], v126 offset:35840
	ds_read_b64_tr_b16 v[208:209], v126 offset:35904
	ds_read_b64_tr_b16 v[212:213], v126 offset:35968
	ds_read_b64_tr_b16 v[216:217], v126 offset:36032
	ds_read_b64_tr_b16 v[116:117], v126 offset:38400
	ds_read_b64_tr_b16 v[210:211], v126 offset:38464
	ds_read_b64_tr_b16 v[214:215], v126 offset:38528
	ds_read_b64_tr_b16 v[218:219], v126 offset:38592
	s_waitcnt lgkmcnt(8)
	v_mfma_f32_32x32x16_bf16 v[2:17], v[240:243], v[118:121], v[2:17]
	v_add_f32_e32 v37, v113, v37
	v_add_f32_e32 v34, v96, v34
	v_add_f32_e32 v35, v97, v35
	s_waitcnt lgkmcnt(3)
	v_mfma_f32_32x32x16_bf16 v[80:95], v[114:117], v[122:125], v[80:95]
	v_add_f32_e32 v36, v98, v36
	v_add_f32_e32 v37, v99, v37
	v_add_f32_e32 v34, v100, v34
	s_waitcnt lgkmcnt(2)
	v_mfma_f32_32x32x16_bf16 v[64:79], v[208:211], v[122:125], v[64:79]
	v_add_f32_e32 v35, v101, v35
	v_add_f32_e32 v36, v102, v36
	v_add_f32_e32 v37, v103, v37
	s_waitcnt lgkmcnt(1)
	v_mfma_f32_32x32x16_bf16 v[48:63], v[212:215], v[122:125], v[48:63]
	ds_read_b64_tr_b16 v[114:115], v126 offset:40960
	ds_read_b64_tr_b16 v[118:119], v126 offset:41024
	ds_read_b64_tr_b16 v[208:209], v126 offset:41088
	ds_read_b64_tr_b16 v[212:213], v126 offset:41152
	ds_read_b64_tr_b16 v[116:117], v126 offset:43520
	ds_read_b64_tr_b16 v[120:121], v126 offset:43584
	ds_read_b64_tr_b16 v[210:211], v126 offset:43648
	ds_read_b64_tr_b16 v[214:215], v126 offset:43712
	s_waitcnt lgkmcnt(8)
	v_mfma_f32_32x32x16_bf16 v[2:17], v[216:219], v[122:125], v[2:17]
	v_add_f32_e32 v34, v104, v34
	v_add_f32_e32 v35, v105, v35
	v_add_f32_e32 v36, v106, v36
	s_waitcnt lgkmcnt(3)
	v_mfma_f32_32x32x16_bf16 v[80:95], v[114:117], v[224:227], v[80:95]
	v_add_f32_e32 v37, v107, v37
	v_add_f32_e32 v34, v108, v34
	v_add_f32_e32 v35, v109, v35
	s_waitcnt lgkmcnt(2)
	v_mfma_f32_32x32x16_bf16 v[64:79], v[118:121], v[224:227], v[64:79]
	v_add_f32_e32 v36, v110, v36
	v_add_f32_e32 v37, v111, v37
	v_add_f32_e32 v34, v35, v34
	s_waitcnt lgkmcnt(1)
	v_mfma_f32_32x32x16_bf16 v[48:63], v[208:211], v[224:227], v[48:63]
	s_waitcnt lgkmcnt(0)
	v_mfma_f32_32x32x16_bf16 v[2:17], v[212:215], v[224:227], v[2:17]
	v_add_f32_e32 v35, v36, v37
	v_add_f32_e32 v34, v35, v34
	v_add_f32_e32 v201, v201, v34
.LBB0_976:
	s_add_i32 s12, s11, 1
	s_cmp_lg_u32 s11, 2
	s_cselect_b32 s11, s12, 0
	s_add_i32 s12, s9, 1
	s_cmp_lg_u32 s9, 2
	s_cselect_b32 s9, s12, 0
	s_add_i32 s10, s10, 1
	s_add_u32 s4, s4, 0x20000
	s_addc_u32 s5, s5, 0
	s_cmp_eq_u32 s4, 0x1080000
	v_lshl_add_u64 v[202:203], v[202:203], 0, s[62:63]
	s_waitcnt lgkmcnt(0)
	s_barrier
	s_cbranch_scc1 .LBB0_978
	v_mov_b32_e32 v208, v32
	s_branch .LBB0_970
